# down-projection epilogue: all 32 bf16 residual loads issued up front with the non-temporal hint (on top of the out-projection ring)
# baseline (speedup 1.0000x reference)
; __device__ __forceinline__ float bf_lo(unsigned w) { return __uint_as_float(w << 16); }
; __device__ __forceinline__ float bf_hi(unsigned w) { return __uint_as_float(w & 0xffff0000u); }
;     __device__ __forceinline__ void fused(f32x4 (&acc)[2][2][4][2], const Unit& u, int wr, int wc, int fr, int fq, LAS unsigned char* lds, int wid, int lane) const {
;         const int row0 = u.pm * BM + wr * 64 + fr, col0 = u.pn * BM + wc * 32 + 4 * fq, b = u.pm >> 3;
;         const float* modb = mod + (size_t)b * NMOD + col0;
;         { f32x4 gv[2][2];
; #pragma unroll
;           for (int bj = 0; bj < 2; ++bj)
; #pragma unroll
;             for (int n = 0; n < 2; ++n) gv[bj][n] = *(const f32x4*)(modb + gate_off + bj * HALF + n * 16);
; #pragma unroll
;           for (int ai = 0; ai < 2; ++ai)
; #pragma unroll
;             for (int m = 0; m < 4; ++m) { const size_t off = (size_t)(row0 + ai * HALF + m * 16) * DM + col0;
; #pragma unroll
;                 for (int bj = 0; bj < 2; ++bj)
; #pragma unroll
;                     for (int n = 0; n < 2; ++n) { const u32x2 xw = *(const u32x2*)(x1b + off + bj * HALF + n * 16); const f32x4 xv = (f32x4){bf_lo(xw.x), bf_hi(xw.x), bf_lo(xw.y), bf_hi(xw.y)};
;                         acc[ai][bj][m][n] = xv + gv[bj][n] * acc[ai][bj][m][n]; }
;                 asm volatile("" : "+v"(acc[ai][0][m][0]), "+v"(acc[ai][0][m][1]), "+v"(acc[ai][1][m][0]), "+v"(acc[ai][1][m][1]));
;                 asm volatile("" ::: "memory"); } }
.LBB0_1125:
	s_add_u32 s0, s34, 0xd200000
	s_addc_u32 s1, s35, 0
	s_lshl_b32 s11, s45, 5
	s_lshl_b32 s10, s43, 8
	s_lshl_b32 s13, s8, 8
	s_add_i32 s12, s10, s50
	s_or_b32 s11, s13, s11
	v_and_or_b32 v144, v136, 12, s11
	v_or_b32_e32 v148, s12, v156
	s_ashr_i32 s11, s43, 3
	v_ashrrev_i32_e32 v149, 31, v148
	s_mul_hi_i32 s13, s11, 0x6000
	s_mulk_i32 s11, 0x6000
	v_ashrrev_i32_e32 v145, 31, v144
	v_lshlrev_b64 v[128:129], 11, v[148:149]
	s_add_u32 s12, s34, s11
	v_lshl_add_u64 v[128:129], s[0:1], 0, v[128:129]
	v_lshlrev_b64 v[150:151], 1, v[144:145]
	s_addc_u32 s13, s35, s13
	v_lshl_add_u64 v[146:147], v[128:129], 0, v[150:151]
	v_lshl_add_u64 v[128:129], v[144:145], 2, s[12:13]
	s_movk_i32 s11, 0x5000
	v_add_co_u32_e32 v128, vcc, s11, v128
	s_barrier
	v_addc_co_u32_e32 v129, vcc, 0, v129, vcc
	global_load_dwordx4 v[140:143], v[128:129], off
	global_load_dwordx4 v[136:139], v[128:129], off offset:64
	global_load_dwordx4 v[132:135], v[128:129], off offset:512
	s_nop 0
	global_load_dwordx4 v[128:131], v[128:129], off offset:576
	global_load_dwordx2 v[176:177], v[146:147], off nt
	global_load_dwordx2 v[178:179], v[146:147], off offset:32 nt
	global_load_dwordx2 v[180:181], v[146:147], off offset:256 nt
	global_load_dwordx2 v[182:183], v[146:147], off offset:288 nt
	s_mov_b64 s[98:99], 0x8000
	v_lshl_add_u64 v[242:243], v[146:147], 0, s[98:99]
	global_load_dwordx2 v[184:185], v[242:243], off nt
	global_load_dwordx2 v[186:187], v[242:243], off offset:32 nt
	global_load_dwordx2 v[188:189], v[242:243], off offset:256 nt
	global_load_dwordx2 v[190:191], v[242:243], off offset:288 nt
	s_mov_b64 s[98:99], 0x10000
	v_lshl_add_u64 v[242:243], v[146:147], 0, s[98:99]
	global_load_dwordx2 v[192:193], v[242:243], off nt
	global_load_dwordx2 v[194:195], v[242:243], off offset:32 nt
	global_load_dwordx2 v[196:197], v[242:243], off offset:256 nt
	global_load_dwordx2 v[198:199], v[242:243], off offset:288 nt
	s_mov_b64 s[98:99], 0x18000
	v_lshl_add_u64 v[242:243], v[146:147], 0, s[98:99]
	global_load_dwordx2 v[200:201], v[242:243], off nt
	global_load_dwordx2 v[202:203], v[242:243], off offset:32 nt
	global_load_dwordx2 v[204:205], v[242:243], off offset:256 nt
	global_load_dwordx2 v[206:207], v[242:243], off offset:288 nt
	s_mov_b64 s[98:99], 0x40000
	v_lshl_add_u64 v[242:243], v[146:147], 0, s[98:99]
	global_load_dwordx2 v[208:209], v[242:243], off nt
	global_load_dwordx2 v[210:211], v[242:243], off offset:32 nt
	global_load_dwordx2 v[212:213], v[242:243], off offset:256 nt
	global_load_dwordx2 v[214:215], v[242:243], off offset:288 nt
	s_mov_b64 s[98:99], 0x48000
	v_lshl_add_u64 v[242:243], v[146:147], 0, s[98:99]
	global_load_dwordx2 v[216:217], v[242:243], off nt
	global_load_dwordx2 v[218:219], v[242:243], off offset:32 nt
	global_load_dwordx2 v[220:221], v[242:243], off offset:256 nt
	global_load_dwordx2 v[222:223], v[242:243], off offset:288 nt
	s_mov_b64 s[98:99], 0x50000
	v_lshl_add_u64 v[242:243], v[146:147], 0, s[98:99]
	global_load_dwordx2 v[224:225], v[242:243], off nt
	global_load_dwordx2 v[226:227], v[242:243], off offset:32 nt
	global_load_dwordx2 v[228:229], v[242:243], off offset:256 nt
	global_load_dwordx2 v[230:231], v[242:243], off offset:288 nt
	s_mov_b64 s[98:99], 0x58000
	v_lshl_add_u64 v[242:243], v[146:147], 0, s[98:99]
	global_load_dwordx2 v[232:233], v[242:243], off nt
	global_load_dwordx2 v[234:235], v[242:243], off offset:32 nt
	global_load_dwordx2 v[236:237], v[242:243], off offset:256 nt
	global_load_dwordx2 v[238:239], v[242:243], off offset:288 nt
	v_or_b32_e32 v164, 16, v148
	v_ashrrev_i32_e32 v165, 31, v164
	v_lshlrev_b64 v[164:165], 11, v[164:165]
	v_lshl_add_u64 v[164:165], s[0:1], 0, v[164:165]
	v_lshl_add_u64 v[164:165], v[164:165], 0, v[150:151]
	s_waitcnt vmcnt(28)
	v_lshlrev_b32_e32 v166, 16, v176
	v_and_b32_e32 v167, 0xffff0000, v176
	v_lshlrev_b32_e32 v154, 16, v177
	v_and_b32_e32 v155, 0xffff0000, v177
	v_lshlrev_b32_e32 v168, 16, v178
	v_and_b32_e32 v169, 0xffff0000, v178
	v_lshlrev_b32_e32 v158, 16, v179
	v_and_b32_e32 v159, 0xffff0000, v179
	v_lshlrev_b32_e32 v172, 16, v180
	v_and_b32_e32 v173, 0xffff0000, v180
	v_lshlrev_b32_e32 v160, 16, v181
	v_and_b32_e32 v161, 0xffff0000, v181
	v_lshlrev_b32_e32 v174, 16, v182
	v_and_b32_e32 v175, 0xffff0000, v182
	v_lshlrev_b32_e32 v162, 16, v183
	v_and_b32_e32 v163, 0xffff0000, v183
	v_pk_fma_f32 v[120:121], v[120:121], v[140:141], v[166:167]
	v_pk_fma_f32 v[122:123], v[122:123], v[142:143], v[154:155]
	v_pk_fma_f32 v[124:125], v[124:125], v[136:137], v[168:169]
	v_pk_fma_f32 v[126:127], v[126:127], v[138:139], v[158:159]
	v_pk_fma_f32 v[116:117], v[116:117], v[132:133], v[172:173]
	v_pk_fma_f32 v[118:119], v[118:119], v[134:135], v[160:161]
	v_pk_fma_f32 v[112:113], v[112:113], v[128:129], v[174:175]
	v_pk_fma_f32 v[114:115], v[114:115], v[130:131], v[162:163]
	s_nop 0
	v_or_b32_e32 v164, 32, v148
	v_ashrrev_i32_e32 v165, 31, v164
	v_lshlrev_b64 v[164:165], 11, v[164:165]
	v_lshl_add_u64 v[164:165], s[0:1], 0, v[164:165]
	v_lshl_add_u64 v[164:165], v[164:165], 0, v[150:151]
	v_or_b32_e32 v148, 48, v148
	v_ashrrev_i32_e32 v149, 31, v148
	v_lshlrev_b64 v[148:149], 11, v[148:149]
	v_lshl_add_u64 v[148:149], s[0:1], 0, v[148:149]
	v_lshl_add_u64 v[148:149], v[148:149], 0, v[150:151]
	s_mov_b32 s0, 0x40000
	v_mul_f32_e32 v153, v125, v125
	v_mul_f32_e32 v157, v127, v127
	v_fmac_f32_e32 v153, v124, v124
	v_fmac_f32_e32 v157, v126, v126
	s_waitcnt vmcnt(24)
; __device__ __forceinline__ float bf_lo(unsigned w) { return __uint_as_float(w << 16); }
; __device__ __forceinline__ float bf_hi(unsigned w) { return __uint_as_float(w & 0xffff0000u); }
;     __device__ __forceinline__ void fused(f32x4 (&acc)[2][2][4][2], const Unit& u, int wr, int wc, int fr, int fq, LAS unsigned char* lds, int wid, int lane) const {
;     ...
;           for (int ai = 0; ai < 2; ++ai)
; #pragma unroll
;             for (int m = 0; m < 4; ++m) { const size_t off = (size_t)(row0 + ai * HALF + m * 16) * DM + col0;
; #pragma unroll
;                 for (int bj = 0; bj < 2; ++bj)
; #pragma unroll
;                     for (int n = 0; n < 2; ++n) { const u32x2 xw = *(const u32x2*)(x1b + off + bj * HALF + n * 16); const f32x4 xv = (f32x4){bf_lo(xw.x), bf_hi(xw.x), bf_lo(xw.y), bf_hi(xw.y)};
;                         acc[ai][bj][m][n] = xv + gv[bj][n] * acc[ai][bj][m][n]; }
;                 asm volatile("" : "+v"(acc[ai][0][m][0]), "+v"(acc[ai][0][m][1]), "+v"(acc[ai][1][m][0]), "+v"(acc[ai][1][m][1]));
	v_lshlrev_b32_e32 v166, 16, v184
	v_and_b32_e32 v167, 0xffff0000, v184
	v_lshlrev_b32_e32 v154, 16, v185
	v_and_b32_e32 v155, 0xffff0000, v185
	v_lshlrev_b32_e32 v168, 16, v186
	v_and_b32_e32 v169, 0xffff0000, v186
	v_lshlrev_b32_e32 v158, 16, v187
	v_and_b32_e32 v159, 0xffff0000, v187
	v_lshlrev_b32_e32 v172, 16, v188
	v_and_b32_e32 v173, 0xffff0000, v188
	v_lshlrev_b32_e32 v160, 16, v189
	v_and_b32_e32 v161, 0xffff0000, v189
	v_lshlrev_b32_e32 v174, 16, v190
	v_and_b32_e32 v175, 0xffff0000, v190
	v_lshlrev_b32_e32 v162, 16, v191
	v_and_b32_e32 v163, 0xffff0000, v191
	v_pk_fma_f32 v[110:111], v[110:111], v[142:143], v[154:155]
	v_pk_fma_f32 v[108:109], v[108:109], v[140:141], v[166:167]
	v_pk_fma_f32 v[106:107], v[106:107], v[138:139], v[158:159]
	v_pk_fma_f32 v[104:105], v[104:105], v[136:137], v[168:169]
	v_pk_fma_f32 v[102:103], v[102:103], v[134:135], v[160:161]
	v_pk_fma_f32 v[100:101], v[100:101], v[132:133], v[172:173]
	v_pk_fma_f32 v[98:99], v[98:99], v[130:131], v[162:163]
	v_pk_fma_f32 v[96:97], v[96:97], v[128:129], v[174:175]
	s_nop 0
	s_waitcnt vmcnt(20)
	v_lshlrev_b32_e32 v150, 16, v192
	v_and_b32_e32 v151, 0xffff0000, v192
	v_lshlrev_b32_e32 v154, 16, v193
	v_and_b32_e32 v155, 0xffff0000, v193
	v_lshlrev_b32_e32 v164, 16, v194
	v_and_b32_e32 v165, 0xffff0000, v194
	v_lshlrev_b32_e32 v158, 16, v195
	v_and_b32_e32 v159, 0xffff0000, v195
	v_lshlrev_b32_e32 v166, 16, v196
	v_and_b32_e32 v167, 0xffff0000, v196
	v_lshlrev_b32_e32 v160, 16, v197
	v_and_b32_e32 v161, 0xffff0000, v197
	v_lshlrev_b32_e32 v168, 16, v198
	v_and_b32_e32 v169, 0xffff0000, v198
	v_lshlrev_b32_e32 v162, 16, v199
	v_and_b32_e32 v163, 0xffff0000, v199
	v_pk_fma_f32 v[94:95], v[94:95], v[142:143], v[154:155]
	v_pk_fma_f32 v[92:93], v[92:93], v[140:141], v[150:151]
	v_pk_fma_f32 v[90:91], v[90:91], v[138:139], v[158:159]
	v_pk_fma_f32 v[88:89], v[88:89], v[136:137], v[164:165]
	v_pk_fma_f32 v[86:87], v[86:87], v[134:135], v[160:161]
	v_pk_fma_f32 v[84:85], v[84:85], v[132:133], v[166:167]
	v_pk_fma_f32 v[82:83], v[82:83], v[130:131], v[162:163]
	v_pk_fma_f32 v[80:81], v[80:81], v[128:129], v[168:169]
	v_add_co_u32_e32 v160, vcc, s0, v146
	s_nop 0
	s_mov_b64 s[0:1], 0x40000
	v_addc_co_u32_e32 v161, vcc, 0, v147, vcc
	s_waitcnt vmcnt(16)
	v_lshlrev_b32_e32 v162, 16, v200
	v_and_b32_e32 v163, 0xffff0000, v200
	v_lshlrev_b32_e32 v150, 16, v201
	v_and_b32_e32 v151, 0xffff0000, v201
	v_lshlrev_b32_e32 v164, 16, v202
	v_and_b32_e32 v165, 0xffff0000, v202
	v_lshlrev_b32_e32 v154, 16, v203
	v_and_b32_e32 v155, 0xffff0000, v203
	v_lshlrev_b32_e32 v166, 16, v204
	v_and_b32_e32 v167, 0xffff0000, v204
	v_lshlrev_b32_e32 v158, 16, v205
	v_and_b32_e32 v159, 0xffff0000, v205
	v_lshlrev_b32_e32 v168, 16, v206
	v_and_b32_e32 v169, 0xffff0000, v206
	v_lshlrev_b32_e32 v148, 16, v207
	v_and_b32_e32 v149, 0xffff0000, v207
	v_pk_fma_f32 v[78:79], v[78:79], v[142:143], v[150:151]
	v_pk_fma_f32 v[76:77], v[76:77], v[140:141], v[162:163]
	v_pk_fma_f32 v[74:75], v[74:75], v[138:139], v[154:155]
	v_pk_fma_f32 v[72:73], v[72:73], v[136:137], v[164:165]
	v_pk_fma_f32 v[70:71], v[70:71], v[134:135], v[158:159]
	v_pk_fma_f32 v[68:69], v[68:69], v[132:133], v[166:167]
	v_pk_fma_f32 v[66:67], v[66:67], v[130:131], v[148:149]
	v_pk_fma_f32 v[64:65], v[64:65], v[128:129], v[168:169]
	v_lshl_add_u64 v[150:151], v[146:147], 0, s[0:1]
	s_nop 0
	s_mov_b32 s0, 0x48000
	v_add_co_u32_e32 v160, vcc, s0, v146
	s_mov_b64 s[0:1], 0x48000
	s_nop 0
	v_addc_co_u32_e32 v161, vcc, 0, v147, vcc
	s_waitcnt vmcnt(12)
	v_lshlrev_b32_e32 v164, 16, v210
	v_lshlrev_b32_e32 v162, 16, v208
	v_and_b32_e32 v163, 0xffff0000, v208
	v_lshlrev_b32_e32 v148, 16, v209
	v_and_b32_e32 v149, 0xffff0000, v209
	v_and_b32_e32 v165, 0xffff0000, v210
	v_lshlrev_b32_e32 v154, 16, v211
	v_and_b32_e32 v155, 0xffff0000, v211
	v_lshlrev_b32_e32 v166, 16, v212
	v_and_b32_e32 v167, 0xffff0000, v212
	v_lshlrev_b32_e32 v158, 16, v213
	v_and_b32_e32 v159, 0xffff0000, v213
	v_lshlrev_b32_e32 v168, 16, v214
	v_and_b32_e32 v169, 0xffff0000, v214
	v_lshlrev_b32_e32 v150, 16, v215
	v_and_b32_e32 v151, 0xffff0000, v215
	v_pk_fma_f32 v[62:63], v[62:63], v[142:143], v[148:149]
	v_pk_fma_f32 v[60:61], v[60:61], v[140:141], v[162:163]
	v_pk_fma_f32 v[58:59], v[58:59], v[138:139], v[154:155]
	v_pk_fma_f32 v[56:57], v[56:57], v[136:137], v[164:165]
	v_pk_fma_f32 v[54:55], v[54:55], v[134:135], v[158:159]
	v_pk_fma_f32 v[52:53], v[52:53], v[132:133], v[166:167]
	v_pk_fma_f32 v[50:51], v[50:51], v[130:131], v[150:151]
	v_pk_fma_f32 v[48:49], v[48:49], v[128:129], v[168:169]
	v_lshl_add_u64 v[150:151], v[146:147], 0, s[0:1]
	s_nop 0
	s_mov_b32 s0, 0x50000
	v_add_co_u32_e32 v160, vcc, s0, v146
	s_mov_b64 s[0:1], 0x50000
	s_nop 0
	v_addc_co_u32_e32 v161, vcc, 0, v147, vcc
	s_waitcnt vmcnt(8)
; __device__ __forceinline__ float bf_lo(unsigned w) { return __uint_as_float(w << 16); }
; __device__ __forceinline__ float bf_hi(unsigned w) { return __uint_as_float(w & 0xffff0000u); }
;     __device__ __forceinline__ void run(const f32x4 (&v)[2][2][4][2], const Unit& u, int wr, int wc, int fr, int fq, LAS unsigned char* lds, int wid, int lane) const {
;     ...
;         for (int ai = 0; ai < 2; ++ai)
; #pragma unroll
;             for (int m = 0; m < 4; ++m) { float s = 0.f;
; #pragma unroll
;                 for (int bj = 0; bj < 2; ++bj)
; #pragma unroll
;                     for (int n = 0; n < 2; ++n) { const f32x4 x = v[ai][bj][m][n]; s += (x[0] * x[0] + x[1] * x[1]) + (x[2] * x[2] + x[3] * x[3]); }
;                 s += __shfl_xor(s, 16); s += __shfl_xor(s, 32);
;                 if (fq == 0) P[(ai * HALF + wr * 64 + m * 16 + fr) * 4 + wc] = s; }
;     __device__ __forceinline__ void fused(f32x4 (&acc)[2][2][4][2], const Unit& u, int wr, int wc, int fr, int fq, LAS unsigned char* lds, int wid, int lane) const {
;     ...
;           for (int ai = 0; ai < 2; ++ai)
; #pragma unroll
;             for (int m = 0; m < 4; ++m) { const size_t off = (size_t)(row0 + ai * HALF + m * 16) * DM + col0;
; #pragma unroll
;                 for (int bj = 0; bj < 2; ++bj)
; #pragma unroll
;                     for (int n = 0; n < 2; ++n) { const u32x2 xw = *(const u32x2*)(x1b + off + bj * HALF + n * 16); const f32x4 xv = (f32x4){bf_lo(xw.x), bf_hi(xw.x), bf_lo(xw.y), bf_hi(xw.y)};
;                         acc[ai][bj][m][n] = xv + gv[bj][n] * acc[ai][bj][m][n]; }
;                 asm volatile("" : "+v"(acc[ai][0][m][0]), "+v"(acc[ai][0][m][1]), "+v"(acc[ai][1][m][0]), "+v"(acc[ai][1][m][1]));
	v_lshlrev_b32_e32 v164, 16, v218
	v_lshlrev_b32_e32 v162, 16, v216
	v_and_b32_e32 v163, 0xffff0000, v216
	v_lshlrev_b32_e32 v148, 16, v217
	v_and_b32_e32 v149, 0xffff0000, v217
	v_and_b32_e32 v165, 0xffff0000, v218
	v_lshlrev_b32_e32 v154, 16, v219
	v_and_b32_e32 v155, 0xffff0000, v219
	v_lshlrev_b32_e32 v166, 16, v220
	v_and_b32_e32 v167, 0xffff0000, v220
	v_lshlrev_b32_e32 v158, 16, v221
	v_and_b32_e32 v159, 0xffff0000, v221
	v_lshlrev_b32_e32 v168, 16, v222
	v_and_b32_e32 v169, 0xffff0000, v222
	v_lshlrev_b32_e32 v150, 16, v223
	v_and_b32_e32 v151, 0xffff0000, v223
	v_pk_fma_f32 v[46:47], v[46:47], v[142:143], v[148:149]
	v_pk_fma_f32 v[44:45], v[44:45], v[140:141], v[162:163]
	v_pk_fma_f32 v[42:43], v[42:43], v[138:139], v[154:155]
	v_pk_fma_f32 v[40:41], v[40:41], v[136:137], v[164:165]
	v_pk_fma_f32 v[38:39], v[38:39], v[134:135], v[158:159]
	v_pk_fma_f32 v[36:37], v[36:37], v[132:133], v[166:167]
	v_pk_fma_f32 v[34:35], v[34:35], v[130:131], v[150:151]
	v_pk_fma_f32 v[32:33], v[32:33], v[128:129], v[168:169]
	v_lshl_add_u64 v[150:151], v[146:147], 0, s[0:1]
	s_nop 0
	s_mov_b32 s0, 0x58000
	v_add_co_u32_e32 v160, vcc, s0, v146
	s_mov_b64 s[0:1], 0x58000
	s_nop 0
	v_addc_co_u32_e32 v161, vcc, 0, v147, vcc
	v_lshl_add_u64 v[146:147], v[146:147], 0, s[0:1]
	s_lshl_b32 s0, s45, 2
	s_add_i32 s11, s0, 0
	s_waitcnt vmcnt(4)
	v_lshlrev_b32_e32 v164, 16, v226
	v_lshlrev_b32_e32 v162, 16, v224
	v_and_b32_e32 v163, 0xffff0000, v224
	v_lshlrev_b32_e32 v148, 16, v225
	v_and_b32_e32 v149, 0xffff0000, v225
	v_and_b32_e32 v165, 0xffff0000, v226
	v_lshlrev_b32_e32 v154, 16, v227
	v_and_b32_e32 v155, 0xffff0000, v227
	v_lshlrev_b32_e32 v166, 16, v228
	v_and_b32_e32 v167, 0xffff0000, v228
	v_lshlrev_b32_e32 v158, 16, v229
	v_and_b32_e32 v159, 0xffff0000, v229
	v_lshlrev_b32_e32 v168, 16, v230
	v_and_b32_e32 v169, 0xffff0000, v230
	v_lshlrev_b32_e32 v150, 16, v231
	v_and_b32_e32 v151, 0xffff0000, v231
	v_pk_fma_f32 v[30:31], v[30:31], v[142:143], v[148:149]
	v_pk_fma_f32 v[28:29], v[28:29], v[140:141], v[162:163]
	v_pk_fma_f32 v[26:27], v[26:27], v[138:139], v[154:155]
	v_pk_fma_f32 v[24:25], v[24:25], v[136:137], v[164:165]
	v_pk_fma_f32 v[22:23], v[22:23], v[134:135], v[158:159]
	v_pk_fma_f32 v[20:21], v[20:21], v[132:133], v[166:167]
	v_pk_fma_f32 v[18:19], v[18:19], v[130:131], v[150:151]
	v_pk_fma_f32 v[16:17], v[16:17], v[128:129], v[168:169]
	v_mul_f32_e32 v150, v121, v121
	s_nop 0
	v_mbcnt_lo_u32_b32 v147, -1, 0
	v_mbcnt_hi_u32_b32 v148, -1, v147
	v_mul_f32_e32 v151, v123, v123
	v_and_b32_e32 v149, 64, v148
	v_mul_f32_e32 v164, v117, v117
	v_mul_f32_e32 v165, v119, v119
	v_fmac_f32_e32 v150, v120, v120
	v_fmac_f32_e32 v151, v122, v122
	v_xor_b32_e32 v147, 16, v148
	v_add_u32_e32 v149, 64, v149
	v_mul_f32_e32 v166, v113, v113
	v_mul_f32_e32 v167, v115, v115
	v_fmac_f32_e32 v164, v116, v116
	v_fmac_f32_e32 v165, v118, v118
	v_add_f32_e32 v150, v150, v151
	v_add_f32_e32 v151, v153, v157
	v_cmp_lt_i32_e32 vcc, v147, v149
	v_fmac_f32_e32 v166, v112, v112
	v_fmac_f32_e32 v167, v114, v114
	v_add_f32_e32 v153, v164, v165
	v_add_f32_e32 v150, v150, v151
	v_cndmask_b32_e32 v147, v148, v147, vcc
	v_add_f32_e32 v157, v166, v167
	v_add_f32_e32 v150, v153, v150
	v_lshlrev_b32_e32 v147, 2, v147
	v_add_f32_e32 v150, v157, v150
	ds_bpermute_b32 v151, v147, v150
	v_xor_b32_e32 v153, 32, v148
	v_cmp_lt_i32_e32 vcc, v153, v149
	v_and_b32_e32 v146, 63, v170
	s_waitcnt lgkmcnt(0)
	v_add_f32_e32 v149, v150, v151
	v_cndmask_b32_e32 v148, v148, v153, vcc
	v_lshlrev_b32_e32 v148, 2, v148
	ds_bpermute_b32 v150, v148, v149
	v_cmp_gt_u32_e32 vcc, 16, v146
	s_waitcnt vmcnt(2)
	v_lshlrev_b32_e32 v166, 16, v234
	v_lshlrev_b32_e32 v164, 16, v232
	v_and_b32_e32 v165, 0xffff0000, v232
	v_lshlrev_b32_e32 v154, 16, v233
	v_and_b32_e32 v155, 0xffff0000, v233
	v_and_b32_e32 v167, 0xffff0000, v234
	v_lshlrev_b32_e32 v158, 16, v235
	v_and_b32_e32 v159, 0xffff0000, v235
	s_waitcnt vmcnt(1)
	v_lshlrev_b32_e32 v168, 16, v236
	v_and_b32_e32 v169, 0xffff0000, v236
	v_lshlrev_b32_e32 v160, 16, v237
	v_and_b32_e32 v161, 0xffff0000, v237
	s_waitcnt vmcnt(0)
	v_lshlrev_b32_e32 v172, 16, v238
	v_and_b32_e32 v173, 0xffff0000, v238
	v_lshlrev_b32_e32 v162, 16, v239
	v_and_b32_e32 v163, 0xffff0000, v239
	v_pk_fma_f32 v[14:15], v[14:15], v[142:143], v[154:155]
	v_pk_fma_f32 v[12:13], v[12:13], v[140:141], v[164:165]
	v_pk_fma_f32 v[10:11], v[10:11], v[138:139], v[158:159]
	v_pk_fma_f32 v[8:9], v[8:9], v[136:137], v[166:167]
	v_pk_fma_f32 v[6:7], v[6:7], v[134:135], v[160:161]
	v_pk_fma_f32 v[4:5], v[4:5], v[132:133], v[168:169]
	v_pk_fma_f32 v[2:3], v[2:3], v[130:131], v[162:163]
	v_pk_fma_f32 v[0:1], v[0:1], v[128:129], v[172:173]
	s_nop 0
	s_and_saveexec_b64 s[0:1], vcc
	v_readlane_b32 s56, v240, 6
	v_readlane_b32 s58, v240, 8
	v_readlane_b32 s57, v240, 7
	v_readlane_b32 s59, v240, 9
	s_cbranch_execz .LBB0_1127
	s_lshl_b32 s12, s44, 10
	s_add_i32 s12, s11, s12
	v_lshl_add_u32 v128, v156, 4, s12
	s_waitcnt lgkmcnt(0)
	v_add_f32_e32 v129, v149, v150
	ds_write_b32 v128, v129
